# dilated-attention softmax: one packed fma per score pair (scale folded into exp2), packed sums, window mask only on the four boundary key tiles (full mask for a segment's first block)
# speedup vs baseline: 1.0043x; 1.0022x over previous
; #define LAS __attribute__((address_space(3)))
; #define MFMA16(a, b, c) __builtin_amdgcn_mfma_f32_16x16x32_bf16((a), (b), (c), 0, 0, 0)
; DI void dil_attn_phase(LAS unsigned char* L, const bf16* Z, const float* cosT, const float* sinT, bf16* OG, float* LSE, int G, int bid, int tid, unsigned long long& tsec) {
;     ...
; #pragma unroll
;         for (int k4 = 0; k4 < 4; ++k4)
; #pragma unroll
;             for (int t5 = 0; t5 < 2; ++t5) { bf16x8 av[5];
; #pragma unroll
;                 for (int tix = 0; tix < 5; ++tix) av[tix] = *(const LAS bf16x8*)(KL + (16 * (tw + 5 * t5 + tix) + fr) * KSTR + (32 * k4 + 8 * fq) * 2);
; #pragma unroll
;                 for (int tix = 0; tix < 5; ++tix) s[5 * t5 + tix] = MFMA16(av[tix], qf[k4], s[5 * t5 + tix]); }
.Lda_loop:
	ds_read_b128 v[58:61], v174 offset:0
	ds_read_b128 v[62:65], v174 offset:4096
	ds_read_b128 v[66:69], v174 offset:8192
	ds_read_b128 v[70:73], v174 offset:12288
	ds_read_b128 v[74:77], v174 offset:16384
	ds_read_b128 v[90:93], v174 offset:20480
	ds_read_b128 v[94:97], v174 offset:24576
	ds_read_b128 v[98:101], v174 offset:28672
	ds_read_b128 v[102:105], v174 offset:32768
	ds_read_b128 v[106:109], v174 offset:36864
	s_waitcnt lgkmcnt(5)
	v_mfma_f32_16x16x32_bf16 v[2:5], v[58:61], v[42:45], 0
	ds_read_b128 v[58:61], v175 offset:0
	v_mfma_f32_16x16x32_bf16 v[6:9], v[62:65], v[42:45], 0
	ds_read_b128 v[62:65], v175 offset:4096
	v_mfma_f32_16x16x32_bf16 v[10:13], v[66:69], v[42:45], 0
	ds_read_b128 v[66:69], v175 offset:8192
	v_mfma_f32_16x16x32_bf16 v[14:17], v[70:73], v[42:45], 0
	ds_read_b128 v[70:73], v175 offset:12288
	v_mfma_f32_16x16x32_bf16 v[18:21], v[74:77], v[42:45], 0
	ds_read_b128 v[74:77], v175 offset:16384
	s_waitcnt lgkmcnt(5)
	v_mfma_f32_16x16x32_bf16 v[22:25], v[90:93], v[42:45], 0
	ds_read_b128 v[90:93], v175 offset:20480
	v_mfma_f32_16x16x32_bf16 v[26:29], v[94:97], v[42:45], 0
	ds_read_b128 v[94:97], v175 offset:24576
	v_mfma_f32_16x16x32_bf16 v[30:33], v[98:101], v[42:45], 0
	ds_read_b128 v[98:101], v175 offset:28672
	v_mfma_f32_16x16x32_bf16 v[34:37], v[102:105], v[42:45], 0
	ds_read_b128 v[102:105], v175 offset:32768
	v_mfma_f32_16x16x32_bf16 v[38:41], v[106:109], v[42:45], 0
	ds_read_b128 v[106:109], v175 offset:36864
	s_waitcnt lgkmcnt(5)
	v_mfma_f32_16x16x32_bf16 v[2:5], v[58:61], v[46:49], v[2:5]
	ds_read_b128 v[58:61], v176 offset:0
	v_mfma_f32_16x16x32_bf16 v[6:9], v[62:65], v[46:49], v[6:9]
	ds_read_b128 v[62:65], v176 offset:4096
	v_mfma_f32_16x16x32_bf16 v[10:13], v[66:69], v[46:49], v[10:13]
	ds_read_b128 v[66:69], v176 offset:8192
	v_mfma_f32_16x16x32_bf16 v[14:17], v[70:73], v[46:49], v[14:17]
	ds_read_b128 v[70:73], v176 offset:12288
	v_mfma_f32_16x16x32_bf16 v[18:21], v[74:77], v[46:49], v[18:21]
	ds_read_b128 v[74:77], v176 offset:16384
	s_waitcnt lgkmcnt(5)
	v_mfma_f32_16x16x32_bf16 v[22:25], v[90:93], v[46:49], v[22:25]
	ds_read_b128 v[90:93], v176 offset:20480
	v_mfma_f32_16x16x32_bf16 v[26:29], v[94:97], v[46:49], v[26:29]
	ds_read_b128 v[94:97], v176 offset:24576
	v_mfma_f32_16x16x32_bf16 v[30:33], v[98:101], v[46:49], v[30:33]
	ds_read_b128 v[98:101], v176 offset:28672
	v_mfma_f32_16x16x32_bf16 v[34:37], v[102:105], v[46:49], v[34:37]
	ds_read_b128 v[102:105], v176 offset:32768
	v_mfma_f32_16x16x32_bf16 v[38:41], v[106:109], v[46:49], v[38:41]
	ds_read_b128 v[106:109], v176 offset:36864
	s_waitcnt lgkmcnt(5)
	v_mfma_f32_16x16x32_bf16 v[2:5], v[58:61], v[50:53], v[2:5]
	ds_read_b128 v[58:61], v177 offset:0
	v_mfma_f32_16x16x32_bf16 v[6:9], v[62:65], v[50:53], v[6:9]
	ds_read_b128 v[62:65], v177 offset:4096
	v_mfma_f32_16x16x32_bf16 v[10:13], v[66:69], v[50:53], v[10:13]
	ds_read_b128 v[66:69], v177 offset:8192
	v_mfma_f32_16x16x32_bf16 v[14:17], v[70:73], v[50:53], v[14:17]
	ds_read_b128 v[70:73], v177 offset:12288
	v_mfma_f32_16x16x32_bf16 v[18:21], v[74:77], v[50:53], v[18:21]
	ds_read_b128 v[74:77], v177 offset:16384
	s_waitcnt lgkmcnt(5)
	v_mfma_f32_16x16x32_bf16 v[22:25], v[90:93], v[50:53], v[22:25]
	ds_read_b128 v[90:93], v177 offset:20480
	v_mfma_f32_16x16x32_bf16 v[26:29], v[94:97], v[50:53], v[26:29]
	ds_read_b128 v[94:97], v177 offset:24576
	v_mfma_f32_16x16x32_bf16 v[30:33], v[98:101], v[50:53], v[30:33]
	ds_read_b128 v[98:101], v177 offset:28672
	v_mfma_f32_16x16x32_bf16 v[34:37], v[102:105], v[50:53], v[34:37]
	ds_read_b128 v[102:105], v177 offset:32768
	v_mfma_f32_16x16x32_bf16 v[38:41], v[106:109], v[50:53], v[38:41]
	ds_read_b128 v[106:109], v177 offset:36864
	s_waitcnt lgkmcnt(5)
	v_mfma_f32_16x16x32_bf16 v[2:5], v[58:61], v[54:57], v[2:5]
	v_mfma_f32_16x16x32_bf16 v[6:9], v[62:65], v[54:57], v[6:9]
	v_mfma_f32_16x16x32_bf16 v[10:13], v[66:69], v[54:57], v[10:13]
	v_mfma_f32_16x16x32_bf16 v[14:17], v[70:73], v[54:57], v[14:17]
	v_mfma_f32_16x16x32_bf16 v[18:21], v[74:77], v[54:57], v[18:21]
	s_waitcnt lgkmcnt(0)
	v_mfma_f32_16x16x32_bf16 v[22:25], v[90:93], v[54:57], v[22:25]
	v_mfma_f32_16x16x32_bf16 v[26:29], v[94:97], v[54:57], v[26:29]
	v_mfma_f32_16x16x32_bf16 v[30:33], v[98:101], v[54:57], v[30:33]
	v_mfma_f32_16x16x32_bf16 v[34:37], v[102:105], v[54:57], v[34:37]
	v_mfma_f32_16x16x32_bf16 v[38:41], v[106:109], v[54:57], v[38:41]
	s_barrier
; DI void dil_attn_phase(LAS unsigned char* L, const bf16* Z, const float* cosT, const float* sinT, bf16* OG, float* LSE, int G, int bid, int tid, unsigned long long& tsec) {
;     ...
;         const float scale = 0.08838834764831845f; float mx = -INFINITY;
; #pragma unroll
;         for (int tix = 0; tix < 10; ++tix)
; #pragma unroll
;             for (int e = 0; e < 4; ++e) { const int kk = 16 * (tw + tix) + 4 * fq + e; const bool ok = (kk >= qi) && (kk <= qi + 128) && (u0 - 128 + kk >= 0);
;                 const float v = ok ? s[tix][e] * scale : -INFINITY; s[tix][e] = v; mx = fmaxf(mx, v); }
	s_add_u32 s6, s5, s22
	s_cmp_lt_u32 s6, 0x600
	s_cselect_b32 s6, s6, s5
	s_and_b32 s41, s6, 31
	s_bfe_u32 s42, s6, 0x20005
	s_lshr_b32 s43, s6, 7
	s_mul_i32 s23, s43, 11
	s_lshr_b32 s23, s23, 5
	s_mul_i32 s25, s23, 3
	s_sub_u32 s25, s43, s25
	s_lshl_b32 s50, s25, 1
	s_lshl_b32 s26, s41, 7
	s_sub_u32 s27, 12, s50
	s_lshr_b32 s27, s26, s27
	s_lshr_b32 s51, 0xfff, s50
	s_and_b32 s51, s26, s51
	s_lshl_b32 s23, s23, 12
	s_add_u32 s23, s23, s27
	s_lshl_b32 s26, s25, 10
	s_lshl_b32 s27, s42, 8
	s_add_u32 s26, s26, s27
	s_mul_i32 s27, s23, 0x2400
	s_add_u32 s27, s27, s26
	s_add_u32 s52, s34, s27
	s_addc_u32 s53, s35, 0
	v_add_u32_e32 v218, s51, v189
	v_lshlrev_b32_e32 v218, s50, v218
	v_mul_u32_u24_e32 v218, 9, v218
	v_lshlrev_b32_e32 v218, 10, v218
	v_lshl_add_u32 v212, v188, 4, v218
	s_add_u32 s44, s52, 3072
	s_addc_u32 s45, s53, 0
	s_sub_u32 s23, s51, 0x80
	v_add_u32_e32 v218, 0, v193
	v_add_u32_e32 v218, s23, v218
	v_max_i32_e32 v218, 0, v218
	v_lshlrev_b32_e32 v218, s50, v218
	v_mul_u32_u24_e32 v218, 9, v218
	v_lshl_add_u32 v218, v218, 10, v198
	s_add_u32 m0, s40, 0
	s_nop 0
	global_load_lds_dwordx4 v218, s[44:45]
	v_add_u32_e32 v218, 4, v193
	v_add_u32_e32 v218, s23, v218
	v_max_i32_e32 v218, 0, v218
	v_lshlrev_b32_e32 v218, s50, v218
	v_mul_u32_u24_e32 v218, 9, v218
	v_lshl_add_u32 v218, v218, 10, v199
	s_add_u32 m0, s40, 1024
	s_nop 0
	global_load_lds_dwordx4 v218, s[44:45]
	v_add_u32_e32 v218, 8, v193
	v_add_u32_e32 v218, s23, v218
	v_max_i32_e32 v218, 0, v218
	v_lshlrev_b32_e32 v218, s50, v218
	v_mul_u32_u24_e32 v218, 9, v218
	v_lshl_add_u32 v218, v218, 10, v200
	s_add_u32 m0, s40, 2048
	s_nop 0
	global_load_lds_dwordx4 v218, s[44:45]
	v_add_u32_e32 v218, 12, v193
	v_add_u32_e32 v218, s23, v218
	v_max_i32_e32 v218, 0, v218
	v_lshlrev_b32_e32 v218, s50, v218
	v_mul_u32_u24_e32 v218, 9, v218
	v_lshl_add_u32 v218, v218, 10, v201
	s_add_u32 m0, s40, 3072
	s_nop 0
	global_load_lds_dwordx4 v218, s[44:45]
	v_add_u32_e32 v218, 16, v193
	v_add_u32_e32 v218, s23, v218
	v_max_i32_e32 v218, 0, v218
	v_lshlrev_b32_e32 v218, s50, v218
	v_mul_u32_u24_e32 v218, 9, v218
	v_lshl_add_u32 v218, v218, 10, v198
	s_add_u32 m0, s40, 4096
	s_nop 0
	global_load_lds_dwordx4 v218, s[44:45]
	v_add_u32_e32 v218, 20, v193
	v_add_u32_e32 v218, s23, v218
	v_max_i32_e32 v218, 0, v218
	v_lshlrev_b32_e32 v218, s50, v218
	v_mul_u32_u24_e32 v218, 9, v218
	v_lshl_add_u32 v218, v218, 10, v199
	s_add_u32 m0, s40, 5120
	s_nop 0
	global_load_lds_dwordx4 v218, s[44:45]
	v_add_u32_e32 v218, 24, v193
	v_add_u32_e32 v218, s23, v218
	v_max_i32_e32 v218, 0, v218
	v_lshlrev_b32_e32 v218, s50, v218
	v_mul_u32_u24_e32 v218, 9, v218
	v_lshl_add_u32 v218, v218, 10, v200
	s_add_u32 m0, s40, 6144
	s_nop 0
	global_load_lds_dwordx4 v218, s[44:45]
	v_add_u32_e32 v218, 28, v193
	v_add_u32_e32 v218, s23, v218
	v_max_i32_e32 v218, 0, v218
	v_lshlrev_b32_e32 v218, s50, v218
	v_mul_u32_u24_e32 v218, 9, v218
	v_lshl_add_u32 v218, v218, 10, v201
	s_add_u32 m0, s40, 7168
	s_nop 0
	global_load_lds_dwordx4 v218, s[44:45]
	global_load_dwordx4 v[42:45], v212, s[52:53]
	global_load_dwordx4 v[46:49], v212, s[52:53] offset:64
	global_load_dwordx4 v[50:53], v212, s[52:53] offset:128
	global_load_dwordx4 v[54:57], v212, s[52:53] offset:192
	s_cmp_eq_u32 s19, 0
	s_cbranch_scc1 .Lda_mfull
	v_add_u32_e32 v218, 0, v215
	v_cmp_ge_u32_e32 vcc, v216, v218
	v_cndmask_b32_e32 v2, v217, v2, vcc
	v_add_u32_e32 v218, 1, v215
	v_cmp_ge_u32_e32 vcc, v216, v218
	v_cndmask_b32_e32 v3, v217, v3, vcc
	v_add_u32_e32 v218, 2, v215
	v_cmp_ge_u32_e32 vcc, v216, v218
	v_cndmask_b32_e32 v4, v217, v4, vcc
	v_add_u32_e32 v218, 3, v215
	v_cmp_ge_u32_e32 vcc, v216, v218
	v_cndmask_b32_e32 v5, v217, v5, vcc
	v_add_u32_e32 v218, 16, v215
	v_cmp_ge_u32_e32 vcc, v216, v218
	v_cndmask_b32_e32 v6, v217, v6, vcc
	v_add_u32_e32 v218, 17, v215
	v_cmp_ge_u32_e32 vcc, v216, v218
	v_cndmask_b32_e32 v7, v217, v7, vcc
	v_add_u32_e32 v218, 18, v215
	v_cmp_ge_u32_e32 vcc, v216, v218
	v_cndmask_b32_e32 v8, v217, v8, vcc
	v_add_u32_e32 v218, 19, v215
	v_cmp_ge_u32_e32 vcc, v216, v218
	v_cndmask_b32_e32 v9, v217, v9, vcc
	v_add_u32_e32 v218, 128, v215
	v_cmp_ge_u32_e32 vcc, v216, v218
	v_cndmask_b32_e32 v34, v217, v34, vcc
	v_add_u32_e32 v218, 129, v215
	v_cmp_ge_u32_e32 vcc, v216, v218
	v_cndmask_b32_e32 v35, v217, v35, vcc
	v_add_u32_e32 v218, 130, v215
	v_cmp_ge_u32_e32 vcc, v216, v218
	v_cndmask_b32_e32 v36, v217, v36, vcc
	v_add_u32_e32 v218, 131, v215
	v_cmp_ge_u32_e32 vcc, v216, v218
	v_cndmask_b32_e32 v37, v217, v37, vcc
	v_add_u32_e32 v218, 144, v215
	v_cmp_ge_u32_e32 vcc, v216, v218
	v_cndmask_b32_e32 v38, v217, v38, vcc
	v_add_u32_e32 v218, 145, v215
	v_cmp_ge_u32_e32 vcc, v216, v218
	v_cndmask_b32_e32 v39, v217, v39, vcc
	v_add_u32_e32 v218, 146, v215
	v_cmp_ge_u32_e32 vcc, v216, v218
	v_cndmask_b32_e32 v40, v217, v40, vcc
	v_add_u32_e32 v218, 147, v215
	v_cmp_ge_u32_e32 vcc, v216, v218
	v_cndmask_b32_e32 v41, v217, v41, vcc
	s_branch .Lda_mdone
; DI void dil_attn_phase(LAS unsigned char* L, const bf16* Z, const float* cosT, const float* sinT, bf16* OG, float* LSE, int G, int bid, int tid, unsigned long long& tsec) {
;     ...
;         const float scale = 0.08838834764831845f; float mx = -INFINITY;
; #pragma unroll
;         for (int tix = 0; tix < 10; ++tix)
; #pragma unroll
;             for (int e = 0; e < 4; ++e) { const int kk = 16 * (tw + tix) + 4 * fq + e; const bool ok = (kk >= qi) && (kk <= qi + 128) && (u0 - 128 + kk >= 0);
;                 const float v = ok ? s[tix][e] * scale : -INFINITY; s[tix][e] = v; mx = fmaxf(mx, v); }
;         mx = fmaxf(mx, __shfl_xor(mx, 16)); mx = fmaxf(mx, __shfl_xor(mx, 32));
.Lda_mfull:
	v_add_u32_e32 v218, 0, v215
	v_cmp_ge_u32_e32 vcc, v216, v218
	v_cndmask_b32_e32 v2, v217, v2, vcc
	v_add_u32_e32 v218, 1, v215
	v_cmp_ge_u32_e32 vcc, v216, v218
	v_cndmask_b32_e32 v3, v217, v3, vcc
	v_add_u32_e32 v218, 2, v215
	v_cmp_ge_u32_e32 vcc, v216, v218
	v_cndmask_b32_e32 v4, v217, v4, vcc
	v_add_u32_e32 v218, 3, v215
	v_cmp_ge_u32_e32 vcc, v216, v218
	v_cndmask_b32_e32 v5, v217, v5, vcc
	v_add_u32_e32 v218, 16, v215
	v_cmp_ge_u32_e32 vcc, v216, v218
	v_cndmask_b32_e32 v6, v217, v6, vcc
	v_add_u32_e32 v218, 17, v215
	v_cmp_ge_u32_e32 vcc, v216, v218
	v_cndmask_b32_e32 v7, v217, v7, vcc
	v_add_u32_e32 v218, 18, v215
	v_cmp_ge_u32_e32 vcc, v216, v218
	v_cndmask_b32_e32 v8, v217, v8, vcc
	v_add_u32_e32 v218, 19, v215
	v_cmp_ge_u32_e32 vcc, v216, v218
	v_cndmask_b32_e32 v9, v217, v9, vcc
	v_add_u32_e32 v218, 32, v215
	v_cmp_ge_u32_e32 vcc, v216, v218
	v_cndmask_b32_e32 v10, v217, v10, vcc
	v_add_u32_e32 v218, 33, v215
	v_cmp_ge_u32_e32 vcc, v216, v218
	v_cndmask_b32_e32 v11, v217, v11, vcc
	v_add_u32_e32 v218, 34, v215
	v_cmp_ge_u32_e32 vcc, v216, v218
	v_cndmask_b32_e32 v12, v217, v12, vcc
	v_add_u32_e32 v218, 35, v215
	v_cmp_ge_u32_e32 vcc, v216, v218
	v_cndmask_b32_e32 v13, v217, v13, vcc
	v_add_u32_e32 v218, 48, v215
	v_cmp_ge_u32_e32 vcc, v216, v218
	v_cndmask_b32_e32 v14, v217, v14, vcc
	v_add_u32_e32 v218, 49, v215
	v_cmp_ge_u32_e32 vcc, v216, v218
	v_cndmask_b32_e32 v15, v217, v15, vcc
	v_add_u32_e32 v218, 50, v215
	v_cmp_ge_u32_e32 vcc, v216, v218
	v_cndmask_b32_e32 v16, v217, v16, vcc
	v_add_u32_e32 v218, 51, v215
	v_cmp_ge_u32_e32 vcc, v216, v218
	v_cndmask_b32_e32 v17, v217, v17, vcc
	v_add_u32_e32 v218, 64, v215
	v_cmp_ge_u32_e32 vcc, v216, v218
	v_cndmask_b32_e32 v18, v217, v18, vcc
	v_add_u32_e32 v218, 65, v215
	v_cmp_ge_u32_e32 vcc, v216, v218
	v_cndmask_b32_e32 v19, v217, v19, vcc
	v_add_u32_e32 v218, 66, v215
	v_cmp_ge_u32_e32 vcc, v216, v218
	v_cndmask_b32_e32 v20, v217, v20, vcc
	v_add_u32_e32 v218, 67, v215
	v_cmp_ge_u32_e32 vcc, v216, v218
	v_cndmask_b32_e32 v21, v217, v21, vcc
	v_add_u32_e32 v218, 80, v215
	v_cmp_ge_u32_e32 vcc, v216, v218
	v_cndmask_b32_e32 v22, v217, v22, vcc
	v_add_u32_e32 v218, 81, v215
	v_cmp_ge_u32_e32 vcc, v216, v218
	v_cndmask_b32_e32 v23, v217, v23, vcc
	v_add_u32_e32 v218, 82, v215
	v_cmp_ge_u32_e32 vcc, v216, v218
	v_cndmask_b32_e32 v24, v217, v24, vcc
	v_add_u32_e32 v218, 83, v215
	v_cmp_ge_u32_e32 vcc, v216, v218
	v_cndmask_b32_e32 v25, v217, v25, vcc
	v_add_u32_e32 v218, 96, v215
	v_cmp_ge_u32_e32 vcc, v216, v218
	v_cndmask_b32_e32 v26, v217, v26, vcc
	v_add_u32_e32 v218, 97, v215
	v_cmp_ge_u32_e32 vcc, v216, v218
	v_cndmask_b32_e32 v27, v217, v27, vcc
	v_add_u32_e32 v218, 98, v215
	v_cmp_ge_u32_e32 vcc, v216, v218
	v_cndmask_b32_e32 v28, v217, v28, vcc
	v_add_u32_e32 v218, 99, v215
	v_cmp_ge_u32_e32 vcc, v216, v218
	v_cndmask_b32_e32 v29, v217, v29, vcc
	v_add_u32_e32 v218, 112, v215
	v_cmp_ge_u32_e32 vcc, v216, v218
	v_cndmask_b32_e32 v30, v217, v30, vcc
	v_add_u32_e32 v218, 113, v215
	v_cmp_ge_u32_e32 vcc, v216, v218
	v_cndmask_b32_e32 v31, v217, v31, vcc
	v_add_u32_e32 v218, 114, v215
	v_cmp_ge_u32_e32 vcc, v216, v218
	v_cndmask_b32_e32 v32, v217, v32, vcc
	v_add_u32_e32 v218, 115, v215
	v_cmp_ge_u32_e32 vcc, v216, v218
	v_cndmask_b32_e32 v33, v217, v33, vcc
	v_add_u32_e32 v218, 128, v215
	v_cmp_ge_u32_e32 vcc, v216, v218
	v_cndmask_b32_e32 v34, v217, v34, vcc
	v_add_u32_e32 v218, 129, v215
	v_cmp_ge_u32_e32 vcc, v216, v218
	v_cndmask_b32_e32 v35, v217, v35, vcc
	v_add_u32_e32 v218, 130, v215
	v_cmp_ge_u32_e32 vcc, v216, v218
	v_cndmask_b32_e32 v36, v217, v36, vcc
	v_add_u32_e32 v218, 131, v215
	v_cmp_ge_u32_e32 vcc, v216, v218
	v_cndmask_b32_e32 v37, v217, v37, vcc
	v_add_u32_e32 v218, 144, v215
	v_cmp_ge_u32_e32 vcc, v216, v218
	v_cndmask_b32_e32 v38, v217, v38, vcc
	v_add_u32_e32 v218, 145, v215
	v_cmp_ge_u32_e32 vcc, v216, v218
	v_cndmask_b32_e32 v39, v217, v39, vcc
	v_add_u32_e32 v218, 146, v215
	v_cmp_ge_u32_e32 vcc, v216, v218
	v_cndmask_b32_e32 v40, v217, v40, vcc
	v_add_u32_e32 v218, 147, v215
	v_cmp_ge_u32_e32 vcc, v216, v218
	v_cndmask_b32_e32 v41, v217, v41, vcc
.Lda_mdone:
	v_max_f32_e32 v225, v2, v3
	v_max3_f32 v225, v225, v4, v5
	v_max3_f32 v225, v225, v6, v7
	v_max3_f32 v225, v225, v8, v9
	v_max3_f32 v225, v225, v10, v11
	v_max3_f32 v225, v225, v12, v13
	v_max3_f32 v225, v225, v14, v15
	v_max3_f32 v225, v225, v16, v17
	v_max3_f32 v225, v225, v18, v19
	v_max3_f32 v225, v225, v20, v21
	v_max3_f32 v225, v225, v22, v23
	v_max3_f32 v225, v225, v24, v25
	v_max3_f32 v225, v225, v26, v27
	v_max3_f32 v225, v225, v28, v29
	v_max3_f32 v225, v225, v30, v31
	v_max3_f32 v225, v225, v32, v33
	v_max3_f32 v225, v225, v34, v35
	v_max3_f32 v225, v225, v36, v37
	v_max3_f32 v225, v225, v38, v39
	v_max3_f32 v225, v225, v40, v41
	ds_bpermute_b32 v218, v191, v225
	s_waitcnt lgkmcnt(0)
	v_max_f32_e32 v218, v218, v218
	v_max_f32_e32 v225, v225, v218
	ds_bpermute_b32 v218, v192, v225
	s_waitcnt lgkmcnt(0)
; DI unsigned pk2(float lo, float hi) { const bf2_t r = __builtin_convertvector((f32x2_t){lo, hi}, bf2_t); return __builtin_bit_cast(unsigned, r); }
; #define DSEC(k) do { if (PROBE_DSEC) { const unsigned long long tn_ = __builtin_amdgcn_s_memrealtime(); if (PROBE_DSEC == (k)) tsec += tn_ - tl_; tl_ = tn_; } } while (0)
; DI void dil_attn_phase(LAS unsigned char* L, const bf16* Z, const float* cosT, const float* sinT, bf16* OG, float* LSE, int G, int bid, int tid, unsigned long long& tsec) {
;     ...
;         mx = fmaxf(mx, __shfl_xor(mx, 16)); mx = fmaxf(mx, __shfl_xor(mx, 32));
;         float den = 0.f;
; #pragma unroll
;         for (int tix = 0; tix < 10; ++tix)
; #pragma unroll
;             for (int e = 0; e < 4; ++e) { const float p = __expf(s[tix][e] - mx); s[tix][e] = p; den += p; }
;         den += __shfl_xor(den, 16); den += __shfl_xor(den, 32);
;         DSEC(5);
;         bf16x8 pf[5];
; #pragma unroll
;         for (int pp = 0; pp < 5; ++pp) { u32x4 pw; pw.x = pk2(s[2 * pp][0], s[2 * pp][1]); pw.y = pk2(s[2 * pp][2], s[2 * pp][3]); pw.z = pk2(s[2 * pp + 1][0], s[2 * pp + 1][1]); pw.w = pk2(s[2 * pp + 1][2], s[2 * pp + 1][3]); pf[pp] = mk8(pw); }
	v_max_f32_e32 v218, v218, v218
	v_max_f32_e32 v225, v225, v218
	v_mov_b32_e32 v220, 0x3e0293ee
	v_mul_f32_e32 v222, v220, v225
	v_mul_f32_e32 v225, 0x3db504f3, v225
	v_pk_fma_f32 v[2:3], v[2:3], v[220:221], v[222:223] op_sel_hi:[1,0,0] neg_lo:[0,0,1] neg_hi:[0,0,1]
	v_pk_fma_f32 v[4:5], v[4:5], v[220:221], v[222:223] op_sel_hi:[1,0,0] neg_lo:[0,0,1] neg_hi:[0,0,1]
	v_pk_fma_f32 v[6:7], v[6:7], v[220:221], v[222:223] op_sel_hi:[1,0,0] neg_lo:[0,0,1] neg_hi:[0,0,1]
	v_pk_fma_f32 v[8:9], v[8:9], v[220:221], v[222:223] op_sel_hi:[1,0,0] neg_lo:[0,0,1] neg_hi:[0,0,1]
	v_pk_fma_f32 v[10:11], v[10:11], v[220:221], v[222:223] op_sel_hi:[1,0,0] neg_lo:[0,0,1] neg_hi:[0,0,1]
	v_pk_fma_f32 v[12:13], v[12:13], v[220:221], v[222:223] op_sel_hi:[1,0,0] neg_lo:[0,0,1] neg_hi:[0,0,1]
	v_pk_fma_f32 v[14:15], v[14:15], v[220:221], v[222:223] op_sel_hi:[1,0,0] neg_lo:[0,0,1] neg_hi:[0,0,1]
	v_pk_fma_f32 v[16:17], v[16:17], v[220:221], v[222:223] op_sel_hi:[1,0,0] neg_lo:[0,0,1] neg_hi:[0,0,1]
	v_pk_fma_f32 v[18:19], v[18:19], v[220:221], v[222:223] op_sel_hi:[1,0,0] neg_lo:[0,0,1] neg_hi:[0,0,1]
	v_pk_fma_f32 v[20:21], v[20:21], v[220:221], v[222:223] op_sel_hi:[1,0,0] neg_lo:[0,0,1] neg_hi:[0,0,1]
	v_pk_fma_f32 v[22:23], v[22:23], v[220:221], v[222:223] op_sel_hi:[1,0,0] neg_lo:[0,0,1] neg_hi:[0,0,1]
	v_pk_fma_f32 v[24:25], v[24:25], v[220:221], v[222:223] op_sel_hi:[1,0,0] neg_lo:[0,0,1] neg_hi:[0,0,1]
	v_pk_fma_f32 v[26:27], v[26:27], v[220:221], v[222:223] op_sel_hi:[1,0,0] neg_lo:[0,0,1] neg_hi:[0,0,1]
	v_pk_fma_f32 v[28:29], v[28:29], v[220:221], v[222:223] op_sel_hi:[1,0,0] neg_lo:[0,0,1] neg_hi:[0,0,1]
	v_pk_fma_f32 v[30:31], v[30:31], v[220:221], v[222:223] op_sel_hi:[1,0,0] neg_lo:[0,0,1] neg_hi:[0,0,1]
	v_pk_fma_f32 v[32:33], v[32:33], v[220:221], v[222:223] op_sel_hi:[1,0,0] neg_lo:[0,0,1] neg_hi:[0,0,1]
	v_pk_fma_f32 v[34:35], v[34:35], v[220:221], v[222:223] op_sel_hi:[1,0,0] neg_lo:[0,0,1] neg_hi:[0,0,1]
	v_pk_fma_f32 v[36:37], v[36:37], v[220:221], v[222:223] op_sel_hi:[1,0,0] neg_lo:[0,0,1] neg_hi:[0,0,1]
	v_pk_fma_f32 v[38:39], v[38:39], v[220:221], v[222:223] op_sel_hi:[1,0,0] neg_lo:[0,0,1] neg_hi:[0,0,1]
	v_pk_fma_f32 v[40:41], v[40:41], v[220:221], v[222:223] op_sel_hi:[1,0,0] neg_lo:[0,0,1] neg_hi:[0,0,1]
	v_exp_f32_e32 v2, v2
	v_exp_f32_e32 v3, v3
	v_exp_f32_e32 v4, v4
	v_exp_f32_e32 v5, v5
	v_exp_f32_e32 v6, v6
	v_exp_f32_e32 v7, v7
	v_exp_f32_e32 v8, v8
	v_exp_f32_e32 v9, v9
	v_exp_f32_e32 v10, v10
	v_exp_f32_e32 v11, v11
	v_exp_f32_e32 v12, v12
	v_exp_f32_e32 v13, v13
	v_exp_f32_e32 v14, v14
	v_exp_f32_e32 v15, v15
	v_exp_f32_e32 v16, v16
	v_exp_f32_e32 v17, v17
	v_exp_f32_e32 v18, v18
	v_exp_f32_e32 v19, v19
	v_exp_f32_e32 v20, v20
	v_exp_f32_e32 v21, v21
	v_exp_f32_e32 v22, v22
	v_exp_f32_e32 v23, v23
	v_exp_f32_e32 v24, v24
	v_exp_f32_e32 v25, v25
	v_exp_f32_e32 v26, v26
	v_exp_f32_e32 v27, v27
	v_exp_f32_e32 v28, v28
	v_exp_f32_e32 v29, v29
	v_exp_f32_e32 v30, v30
	v_exp_f32_e32 v31, v31
	v_exp_f32_e32 v32, v32
	v_exp_f32_e32 v33, v33
	v_exp_f32_e32 v34, v34
	v_exp_f32_e32 v35, v35
	v_exp_f32_e32 v36, v36
	v_exp_f32_e32 v37, v37
	v_exp_f32_e32 v38, v38
	v_exp_f32_e32 v39, v39
	v_exp_f32_e32 v40, v40
	v_exp_f32_e32 v41, v41
	s_nop 0
	v_pk_add_f32 v[226:227], v[2:3], v[4:5]
	v_pk_add_f32 v[226:227], v[6:7], v[226:227]
	v_pk_add_f32 v[226:227], v[8:9], v[226:227]
	v_pk_add_f32 v[226:227], v[10:11], v[226:227]
	v_pk_add_f32 v[226:227], v[12:13], v[226:227]
	v_pk_add_f32 v[226:227], v[14:15], v[226:227]
	v_pk_add_f32 v[226:227], v[16:17], v[226:227]
	v_pk_add_f32 v[226:227], v[18:19], v[226:227]
	v_pk_add_f32 v[226:227], v[20:21], v[226:227]
	v_pk_add_f32 v[226:227], v[22:23], v[226:227]
	v_pk_add_f32 v[226:227], v[24:25], v[226:227]
	v_pk_add_f32 v[226:227], v[26:27], v[226:227]
	v_pk_add_f32 v[226:227], v[28:29], v[226:227]
	v_pk_add_f32 v[226:227], v[30:31], v[226:227]
	v_pk_add_f32 v[226:227], v[32:33], v[226:227]
	v_pk_add_f32 v[226:227], v[34:35], v[226:227]
	v_pk_add_f32 v[226:227], v[36:37], v[226:227]
	v_pk_add_f32 v[226:227], v[38:39], v[226:227]
	v_pk_add_f32 v[226:227], v[40:41], v[226:227]
	v_add_f32_e32 v226, v226, v227
	ds_bpermute_b32 v218, v191, v226
	s_waitcnt lgkmcnt(0)
	v_add_f32_e32 v226, v226, v218
	ds_bpermute_b32 v218, v192, v226
	s_waitcnt lgkmcnt(0)
	v_add_f32_e32 v226, v226, v218
	v_rcp_f32_e32 v224, v226
	v_cvt_pk_bf16_f32 v122, v2, v3
	v_cvt_pk_bf16_f32 v123, v4, v5
	v_cvt_pk_bf16_f32 v124, v6, v7
	v_cvt_pk_bf16_f32 v125, v8, v9
	v_cvt_pk_bf16_f32 v126, v10, v11
	v_cvt_pk_bf16_f32 v127, v12, v13
	v_cvt_pk_bf16_f32 v128, v14, v15
	v_cvt_pk_bf16_f32 v129, v16, v17
	v_cvt_pk_bf16_f32 v130, v18, v19
	v_cvt_pk_bf16_f32 v131, v20, v21
	v_cvt_pk_bf16_f32 v132, v22, v23
	v_cvt_pk_bf16_f32 v133, v24, v25
	v_cvt_pk_bf16_f32 v134, v26, v27
	v_cvt_pk_bf16_f32 v135, v28, v29
	v_cvt_pk_bf16_f32 v136, v30, v31
	v_cvt_pk_bf16_f32 v137, v32, v33
	v_cvt_pk_bf16_f32 v138, v34, v35
	v_cvt_pk_bf16_f32 v139, v36, v37
	v_cvt_pk_bf16_f32 v140, v38, v39
	v_cvt_pk_bf16_f32 v141, v40, v41
	s_waitcnt vmcnt(12)
	s_barrier
; #define LAS __attribute__((address_space(3)))
; #define MFMA16(a, b, c) __builtin_amdgcn_mfma_f32_16x16x32_bf16((a), (b), (c), 0, 0, 0)
; DI void dil_attn_phase(LAS unsigned char* L, const bf16* Z, const float* cosT, const float* sinT, bf16* OG, float* LSE, int G, int bid, int tid, unsigned long long& tsec) {
;     ...
;         const unsigned x0 = (unsigned)(fq ^ (fr >> 3));
;         const LAS unsigned char* vev = L + KL_BYTES + fr * VSTR + 32 * tw + (x0 << 3); const LAS unsigned char* vod = L + KL_BYTES + fr * VSTR + 32 * tw + ((x0 ^ 2u) << 3);
; #pragma unroll
;         for (int pp = 0; pp < 5; ++pp)
; #pragma unroll
;             for (int d4 = 0; d4 < 2; ++d4) { bf16x8 vf[4];
; #pragma unroll
;                 for (int dq = 0; dq < 4; ++dq) { const int dt = 4 * d4 + dq; const LAS unsigned char* vb_ = ((dt & 1) ? vod : vev) + 16 * dt * VSTR + 64 * pp;
;                     const s16x4 lo = *(const LAS s16x4*)(vb_ + (((2 * dt) & 4) << 3)), hi = *(const LAS s16x4*)(vb_ + ((((2 * dt) & 4) ^ 4) << 3)); vf[dq] = __builtin_shufflevector(lo, hi, 0, 1, 2, 3, 4, 5, 6, 7); }
; #pragma unroll
;                 for (int dq = 0; dq < 4; ++dq) o[4 * d4 + dq] = MFMA16(vf[dq], pf[pp], o[4 * d4 + dq]);
;             }
	ds_read_b64_tr_b16 v[58:59], v178 offset:0
	ds_read_b64_tr_b16 v[60:61], v178 offset:4096
	ds_read_b64_tr_b16 v[62:63], v179 offset:0
	ds_read_b64_tr_b16 v[64:65], v179 offset:4096
	ds_read_b64_tr_b16 v[66:67], v180 offset:0
	ds_read_b64_tr_b16 v[68:69], v180 offset:4096
	ds_read_b64_tr_b16 v[70:71], v181 offset:0
	ds_read_b64_tr_b16 v[72:73], v181 offset:4096
	ds_read_b64_tr_b16 v[74:75], v182 offset:0
	ds_read_b64_tr_b16 v[76:77], v182 offset:4096
	ds_read_b64_tr_b16 v[78:79], v183 offset:0
	ds_read_b64_tr_b16 v[80:81], v183 offset:4096
	ds_read_b64_tr_b16 v[82:83], v184 offset:0
	ds_read_b64_tr_b16 v[84:85], v184 offset:4096
	ds_read_b64_tr_b16 v[86:87], v185 offset:0
	ds_read_b64_tr_b16 v[88:89], v185 offset:4096
	ds_read_b64_tr_b16 v[90:91], v178 offset:8192
	ds_read_b64_tr_b16 v[92:93], v178 offset:12288
	ds_read_b64_tr_b16 v[94:95], v179 offset:8192
	ds_read_b64_tr_b16 v[96:97], v179 offset:12288
	ds_read_b64_tr_b16 v[98:99], v180 offset:8192
	ds_read_b64_tr_b16 v[100:101], v180 offset:12288
	ds_read_b64_tr_b16 v[102:103], v181 offset:8192
	ds_read_b64_tr_b16 v[104:105], v181 offset:12288
	ds_read_b64_tr_b16 v[106:107], v182 offset:8192
	ds_read_b64_tr_b16 v[108:109], v182 offset:12288
	ds_read_b64_tr_b16 v[110:111], v183 offset:8192
	ds_read_b64_tr_b16 v[112:113], v183 offset:12288
	ds_read_b64_tr_b16 v[114:115], v184 offset:8192
	ds_read_b64_tr_b16 v[116:117], v184 offset:12288
	ds_read_b64_tr_b16 v[118:119], v185 offset:8192
	ds_read_b64_tr_b16 v[120:121], v185 offset:12288
	s_waitcnt lgkmcnt(15)
	v_mfma_f32_16x16x32_bf16 v[142:145], v[58:61], v[122:125], 0
	ds_read_b64_tr_b16 v[58:59], v178 offset:16384
	ds_read_b64_tr_b16 v[60:61], v178 offset:20480
	v_mfma_f32_16x16x32_bf16 v[146:149], v[62:65], v[122:125], 0
	ds_read_b64_tr_b16 v[62:63], v179 offset:16384
	ds_read_b64_tr_b16 v[64:65], v179 offset:20480
	v_mfma_f32_16x16x32_bf16 v[150:153], v[66:69], v[122:125], 0
	ds_read_b64_tr_b16 v[66:67], v180 offset:16384
	ds_read_b64_tr_b16 v[68:69], v180 offset:20480
	v_mfma_f32_16x16x32_bf16 v[154:157], v[70:73], v[122:125], 0
	ds_read_b64_tr_b16 v[70:71], v181 offset:16384
	ds_read_b64_tr_b16 v[72:73], v181 offset:20480
	v_mfma_f32_16x16x32_bf16 v[158:161], v[74:77], v[122:125], 0
	ds_read_b64_tr_b16 v[74:75], v182 offset:16384
	ds_read_b64_tr_b16 v[76:77], v182 offset:20480
	v_mfma_f32_16x16x32_bf16 v[162:165], v[78:81], v[122:125], 0
	ds_read_b64_tr_b16 v[78:79], v183 offset:16384
	ds_read_b64_tr_b16 v[80:81], v183 offset:20480
	v_mfma_f32_16x16x32_bf16 v[166:169], v[82:85], v[122:125], 0
	ds_read_b64_tr_b16 v[82:83], v184 offset:16384
	ds_read_b64_tr_b16 v[84:85], v184 offset:20480
	v_mfma_f32_16x16x32_bf16 v[170:173], v[86:89], v[122:125], 0
	ds_read_b64_tr_b16 v[86:87], v185 offset:16384
	ds_read_b64_tr_b16 v[88:89], v185 offset:20480
	s_waitcnt lgkmcnt(15)
	v_mfma_f32_16x16x32_bf16 v[142:145], v[90:93], v[126:129], v[142:145]
	ds_read_b64_tr_b16 v[90:91], v178 offset:24576
	ds_read_b64_tr_b16 v[92:93], v178 offset:28672
	v_mfma_f32_16x16x32_bf16 v[146:149], v[94:97], v[126:129], v[146:149]
	ds_read_b64_tr_b16 v[94:95], v179 offset:24576
	ds_read_b64_tr_b16 v[96:97], v179 offset:28672
	v_mfma_f32_16x16x32_bf16 v[150:153], v[98:101], v[126:129], v[150:153]
	ds_read_b64_tr_b16 v[98:99], v180 offset:24576
	ds_read_b64_tr_b16 v[100:101], v180 offset:28672
	v_mfma_f32_16x16x32_bf16 v[154:157], v[102:105], v[126:129], v[154:157]
	ds_read_b64_tr_b16 v[102:103], v181 offset:24576
	ds_read_b64_tr_b16 v[104:105], v181 offset:28672
	v_mfma_f32_16x16x32_bf16 v[158:161], v[106:109], v[126:129], v[158:161]
	ds_read_b64_tr_b16 v[106:107], v182 offset:24576
	ds_read_b64_tr_b16 v[108:109], v182 offset:28672
	v_mfma_f32_16x16x32_bf16 v[162:165], v[110:113], v[126:129], v[162:165]
	ds_read_b64_tr_b16 v[110:111], v183 offset:24576
	ds_read_b64_tr_b16 v[112:113], v183 offset:28672
	v_mfma_f32_16x16x32_bf16 v[166:169], v[114:117], v[126:129], v[166:169]
	ds_read_b64_tr_b16 v[114:115], v184 offset:24576
	ds_read_b64_tr_b16 v[116:117], v184 offset:28672
	v_mfma_f32_16x16x32_bf16 v[170:173], v[118:121], v[126:129], v[170:173]
	ds_read_b64_tr_b16 v[118:119], v185 offset:24576
	ds_read_b64_tr_b16 v[120:121], v185 offset:28672
	s_waitcnt lgkmcnt(15)
	v_mfma_f32_16x16x32_bf16 v[142:145], v[58:61], v[130:133], v[142:145]
	ds_read_b64_tr_b16 v[58:59], v178 offset:32768
	ds_read_b64_tr_b16 v[60:61], v178 offset:36864
	v_mfma_f32_16x16x32_bf16 v[146:149], v[62:65], v[130:133], v[146:149]
	ds_read_b64_tr_b16 v[62:63], v179 offset:32768
	ds_read_b64_tr_b16 v[64:65], v179 offset:36864
	v_mfma_f32_16x16x32_bf16 v[150:153], v[66:69], v[130:133], v[150:153]
	ds_read_b64_tr_b16 v[66:67], v180 offset:32768
	ds_read_b64_tr_b16 v[68:69], v180 offset:36864
	v_mfma_f32_16x16x32_bf16 v[154:157], v[70:73], v[130:133], v[154:157]
	ds_read_b64_tr_b16 v[70:71], v181 offset:32768
	ds_read_b64_tr_b16 v[72:73], v181 offset:36864
	v_mfma_f32_16x16x32_bf16 v[158:161], v[74:77], v[130:133], v[158:161]
	ds_read_b64_tr_b16 v[74:75], v182 offset:32768
	ds_read_b64_tr_b16 v[76:77], v182 offset:36864
	v_mfma_f32_16x16x32_bf16 v[162:165], v[78:81], v[130:133], v[162:165]
	ds_read_b64_tr_b16 v[78:79], v183 offset:32768
	ds_read_b64_tr_b16 v[80:81], v183 offset:36864
	v_mfma_f32_16x16x32_bf16 v[166:169], v[82:85], v[130:133], v[166:169]
	ds_read_b64_tr_b16 v[82:83], v184 offset:32768
	ds_read_b64_tr_b16 v[84:85], v184 offset:36864
	v_mfma_f32_16x16x32_bf16 v[170:173], v[86:89], v[130:133], v[170:173]
	ds_read_b64_tr_b16 v[86:87], v185 offset:32768
	ds_read_b64_tr_b16 v[88:89], v185 offset:36864
	s_waitcnt lgkmcnt(15)
	v_mfma_f32_16x16x32_bf16 v[142:145], v[90:93], v[134:137], v[142:145]
	v_mfma_f32_16x16x32_bf16 v[146:149], v[94:97], v[134:137], v[146:149]
	v_mfma_f32_16x16x32_bf16 v[150:153], v[98:101], v[134:137], v[150:153]
	v_mfma_f32_16x16x32_bf16 v[154:157], v[102:105], v[134:137], v[154:157]
	v_mfma_f32_16x16x32_bf16 v[158:161], v[106:109], v[134:137], v[158:161]
	v_mfma_f32_16x16x32_bf16 v[162:165], v[110:113], v[134:137], v[162:165]
	v_mfma_f32_16x16x32_bf16 v[166:169], v[114:117], v[134:137], v[166:169]
	v_mfma_f32_16x16x32_bf16 v[170:173], v[118:121], v[134:137], v[170:173]
	s_waitcnt lgkmcnt(0)
	v_mfma_f32_16x16x32_bf16 v[142:145], v[58:61], v[138:141], v[142:145]
	v_mfma_f32_16x16x32_bf16 v[146:149], v[62:65], v[138:141], v[146:149]
	v_mfma_f32_16x16x32_bf16 v[150:153], v[66:69], v[138:141], v[150:153]
	v_mfma_f32_16x16x32_bf16 v[154:157], v[70:73], v[138:141], v[154:157]
	v_mfma_f32_16x16x32_bf16 v[158:161], v[74:77], v[138:141], v[158:161]
	v_mfma_f32_16x16x32_bf16 v[162:165], v[78:81], v[138:141], v[162:165]
	v_mfma_f32_16x16x32_bf16 v[166:169], v[82:85], v[138:141], v[166:169]
	v_mfma_f32_16x16x32_bf16 v[170:173], v[86:89], v[138:141], v[170:173]
	s_barrier
; DI unsigned pk2(float lo, float hi) { const bf2_t r = __builtin_convertvector((f32x2_t){lo, hi}, bf2_t); return __builtin_bit_cast(unsigned, r); }
; DI void dil_attn_phase(LAS unsigned char* L, const bf16* Z, const float* cosT, const float* sinT, bf16* OG, float* LSE, int G, int bid, int tid, unsigned long long& tsec) {
;     ...
;     if (bid < 1536) DIL_LOAD(bid);
;     for (int unit = bid; unit < 1536; unit += G) {
;         const int j = unit & 31, h = (unit >> 5) & 3, gb = unit >> 7, g = gb % 3, b = gb / 3;
;         const int dsh = 2 * g, Lseg = T >> dsh;
;         const int p0 = 128 * j, r = p0 / Lseg, u0 = p0 & (Lseg - 1);
;         const int tokbase = b * T + r;
;         const int colq = g * 512 + h * 128;
;         asm volatile("" : "+v"(kreg[0]), "+v"(kreg[1]), "+v"(kreg[2]), "+v"(kreg[3]), "+v"(kreg[4]), "+v"(kreg[5]), "+v"(kreg[6]), "+v"(kreg[7]));
;         asm volatile("" : "+v"(vreg[0]), "+v"(vreg[1]), "+v"(vreg[2]), "+v"(vreg[3]), "+v"(vreg[4]), "+v"(vreg[5]), "+v"(vreg[6]), "+v"(vreg[7]));
;         const int qi = 16 * wid + fr; const size_t tq = (size_t)(tokbase + ((u0 + qi) << dsh));
;     ...
;         const float inv = __builtin_amdgcn_rcpf(den), lse = mx + __logf(den);
;         { bf16* op = OG + tq * 1536 + colq + 4 * fq;
; #pragma unroll
;           for (int dt = 0; dt < 8; ++dt) *(unsigned long long*)(op + 16 * dt) = (unsigned long long)pk2(o[dt][0] * inv, o[dt][1] * inv) | ((unsigned long long)pk2(o[dt][2] * inv, o[dt][3] * inv) << 32); }
;         if (lane < 16) LSE[tq * 12 + g * 4 + h] = lse;
	s_add_u32 s44, s52, 6144
	s_addc_u32 s45, s53, 0
	s_sub_u32 s23, s51, 0x80
	v_add_u32_e32 v218, 0, v193
	v_add_u32_e32 v218, s23, v218
	v_max_i32_e32 v218, 0, v218
	v_lshlrev_b32_e32 v218, s50, v218
	v_mul_u32_u24_e32 v218, 9, v218
	v_lshl_add_u32 v218, v218, 10, v206
	s_add_u32 m0, s40, 65536
	s_nop 0
	global_load_lds_dwordx4 v218, s[44:45]
	v_add_u32_e32 v218, 4, v193
	v_add_u32_e32 v218, s23, v218
	v_max_i32_e32 v218, 0, v218
	v_lshlrev_b32_e32 v218, s50, v218
	v_mul_u32_u24_e32 v218, 9, v218
	v_lshl_add_u32 v218, v218, 10, v207
	s_add_u32 m0, s40, 66560
	s_nop 0
	global_load_lds_dwordx4 v218, s[44:45]
	v_add_u32_e32 v218, 8, v193
	v_add_u32_e32 v218, s23, v218
	v_max_i32_e32 v218, 0, v218
	v_lshlrev_b32_e32 v218, s50, v218
	v_mul_u32_u24_e32 v218, 9, v218
	v_lshl_add_u32 v218, v218, 10, v208
	s_add_u32 m0, s40, 67584
	s_nop 0
	global_load_lds_dwordx4 v218, s[44:45]
	v_add_u32_e32 v218, 12, v193
	v_add_u32_e32 v218, s23, v218
	v_max_i32_e32 v218, 0, v218
	v_lshlrev_b32_e32 v218, s50, v218
	v_mul_u32_u24_e32 v218, 9, v218
	v_lshl_add_u32 v218, v218, 10, v209
	s_add_u32 m0, s40, 68608
	s_nop 0
	global_load_lds_dwordx4 v218, s[44:45]
	v_add_u32_e32 v218, 16, v193
	v_add_u32_e32 v218, s23, v218
	v_max_i32_e32 v218, 0, v218
	v_lshlrev_b32_e32 v218, s50, v218
	v_mul_u32_u24_e32 v218, 9, v218
	v_lshl_add_u32 v218, v218, 10, v206
	s_add_u32 m0, s40, 69632
	s_nop 0
	global_load_lds_dwordx4 v218, s[44:45]
	v_add_u32_e32 v218, 20, v193
	v_add_u32_e32 v218, s23, v218
	v_max_i32_e32 v218, 0, v218
	v_lshlrev_b32_e32 v218, s50, v218
	v_mul_u32_u24_e32 v218, 9, v218
	v_lshl_add_u32 v218, v218, 10, v207
	s_add_u32 m0, s40, 70656
	s_nop 0
	global_load_lds_dwordx4 v218, s[44:45]
	v_add_u32_e32 v218, 24, v193
	v_add_u32_e32 v218, s23, v218
	v_max_i32_e32 v218, 0, v218
	v_lshlrev_b32_e32 v218, s50, v218
	v_mul_u32_u24_e32 v218, 9, v218
	v_lshl_add_u32 v218, v218, 10, v208
	s_add_u32 m0, s40, 71680
	s_nop 0
	global_load_lds_dwordx4 v218, s[44:45]
	v_add_u32_e32 v218, 28, v193
	v_add_u32_e32 v218, s23, v218
	v_max_i32_e32 v218, 0, v218
	v_lshlrev_b32_e32 v218, s50, v218
	v_mul_u32_u24_e32 v218, 9, v218
	v_lshl_add_u32 v218, v218, 10, v209
	s_add_u32 m0, s40, 72704
	s_nop 0
	global_load_lds_dwordx4 v218, s[44:45]
	v_pk_mul_f32 v[142:143], v[142:143], v[224:225] op_sel_hi:[1,0]
	v_pk_mul_f32 v[144:145], v[144:145], v[224:225] op_sel_hi:[1,0]
	v_cvt_pk_bf16_f32 v142, v142, v143
	v_cvt_pk_bf16_f32 v143, v144, v145
	global_store_dwordx2 v213, v[142:143], s[14:15]
	v_pk_mul_f32 v[146:147], v[146:147], v[224:225] op_sel_hi:[1,0]
	v_pk_mul_f32 v[148:149], v[148:149], v[224:225] op_sel_hi:[1,0]
	v_cvt_pk_bf16_f32 v146, v146, v147
	v_cvt_pk_bf16_f32 v147, v148, v149
	global_store_dwordx2 v213, v[146:147], s[14:15] offset:32
	v_pk_mul_f32 v[150:151], v[150:151], v[224:225] op_sel_hi:[1,0]
	v_pk_mul_f32 v[152:153], v[152:153], v[224:225] op_sel_hi:[1,0]
	v_cvt_pk_bf16_f32 v150, v150, v151
	v_cvt_pk_bf16_f32 v151, v152, v153
	global_store_dwordx2 v213, v[150:151], s[14:15] offset:64
	v_pk_mul_f32 v[154:155], v[154:155], v[224:225] op_sel_hi:[1,0]
	v_pk_mul_f32 v[156:157], v[156:157], v[224:225] op_sel_hi:[1,0]
	v_cvt_pk_bf16_f32 v154, v154, v155
	v_cvt_pk_bf16_f32 v155, v156, v157
	global_store_dwordx2 v213, v[154:155], s[14:15] offset:96
	v_pk_mul_f32 v[158:159], v[158:159], v[224:225] op_sel_hi:[1,0]
	v_pk_mul_f32 v[160:161], v[160:161], v[224:225] op_sel_hi:[1,0]
	v_cvt_pk_bf16_f32 v158, v158, v159
	v_cvt_pk_bf16_f32 v159, v160, v161
	global_store_dwordx2 v213, v[158:159], s[14:15] offset:128
	v_pk_mul_f32 v[162:163], v[162:163], v[224:225] op_sel_hi:[1,0]
	v_pk_mul_f32 v[164:165], v[164:165], v[224:225] op_sel_hi:[1,0]
	v_cvt_pk_bf16_f32 v162, v162, v163
	v_cvt_pk_bf16_f32 v163, v164, v165
	global_store_dwordx2 v213, v[162:163], s[14:15] offset:160
	v_pk_mul_f32 v[166:167], v[166:167], v[224:225] op_sel_hi:[1,0]
	v_pk_mul_f32 v[168:169], v[168:169], v[224:225] op_sel_hi:[1,0]
	v_cvt_pk_bf16_f32 v166, v166, v167
	v_cvt_pk_bf16_f32 v167, v168, v169
	global_store_dwordx2 v213, v[166:167], s[14:15] offset:192
	v_pk_mul_f32 v[170:171], v[170:171], v[224:225] op_sel_hi:[1,0]
	v_pk_mul_f32 v[172:173], v[172:173], v[224:225] op_sel_hi:[1,0]
	v_cvt_pk_bf16_f32 v170, v170, v171
	v_cvt_pk_bf16_f32 v171, v172, v173
	global_store_dwordx2 v213, v[170:171], s[14:15] offset:224
	v_log_f32_e32 v218, v226
	s_nop 0
	v_mul_f32_e32 v219, 0x3f317217, v218
	v_fma_f32 v219, v218, s48, -v219
	v_fmac_f32_e32 v219, 0x3377d1cf, v218
	v_fmac_f32_e32 v219, 0x3f317217, v218
	v_add_f32_e32 v219, v225, v219
	v_cmp_eq_u32_e32 vcc, 0, v188
	s_and_saveexec_b64 s[54:55], vcc
	global_store_dword v214, v219, s[16:17]
	s_mov_b64 exec, s[54:55]
	s_add_u32 s23, s5, s22
	s_cmp_lt_u32 s23, 0x600
	s_cbranch_scc0 .Lda_done
	s_mov_b32 s5, s23
	s_and_b32 s41, s5, 31
	s_bfe_u32 s42, s5, 0x20005
	s_lshr_b32 s43, s5, 7
	s_mul_i32 s23, s43, 11
	s_lshr_b32 s23, s23, 5
	s_mul_i32 s25, s23, 3
	s_sub_u32 s25, s43, s25
	s_lshl_b32 s50, s25, 1
	s_lshl_b32 s26, s41, 7
	s_sub_u32 s27, 12, s50
	s_lshr_b32 s27, s26, s27
	s_lshr_b32 s51, 0xfff, s50
	s_and_b32 s51, s26, s51
	s_lshl_b32 s23, s23, 12
	s_add_u32 s23, s23, s27
	s_lshl_b32 s26, s25, 10
	s_lshl_b32 s27, s42, 8
	s_add_u32 s26, s26, s27
	s_mul_i32 s27, s23, 0x2400
	s_add_u32 s27, s27, s26
	s_add_u32 s52, s34, s27
	s_addc_u32 s53, s35, 0
	s_mov_b32 s18, s50
	s_mov_b32 s19, s51
	s_mul_i32 s27, s23, 0xc00
	s_add_u32 s27, s27, s26
	s_add_u32 s14, s36, s27
	s_addc_u32 s15, s37, 0
	s_mul_i32 s27, s23, 48
	s_lshl_b32 s26, s25, 4
	s_lshl_b32 s23, s42, 2
	s_add_u32 s26, s26, s23
	s_add_u32 s27, s27, s26
	s_add_u32 s16, s38, s27
	s_addc_u32 s17, s39, 0
	v_add_u32_e32 v218, s19, v189
	v_lshlrev_b32_e32 v218, s18, v218
	v_mul_u32_u24_e32 v219, 3, v218
	v_lshlrev_b32_e32 v219, 10, v219
	v_lshl_add_u32 v213, v188, 3, v219
	v_mul_u32_u24_e32 v214, 48, v218
	s_cmp_eq_u32 s19, 0
	s_cselect_b32 s23, 0x80, 0
	v_max_u32_e32 v219, s23, v189
	v_sub_u32_e32 v215, v190, v219
	v_sub_u32_e32 v216, v189, v219
	v_add_u32_e32 v216, 0x80, v216
	s_waitcnt vmcnt(17)
	s_barrier
	s_branch .Lda_loop
